# phase 3 virtual block ids: SSD-sample chains moved to blocks 256..319 (CU partners of DN-sample chains if b and b+256 co-reside)
# speedup vs baseline: 1.0118x; 1.0118x over previous
.LBB0_403:
	s_add_i32 vcc_lo, s84, 0xffffffc0
	s_cmp_lt_u32 vcc_lo, 64
	s_cbranch_scc0 .Lperma_1
	s_addk_i32 s84, 0xc0
	s_branch .Lperma_2
.Lperma_1:
	s_add_i32 vcc_lo, s84, 0xffffff00
	s_cmp_lt_u32 vcc_lo, 64
	s_cbranch_scc0 .Lperma_2
	s_addk_i32 s84, 0xff40
.Lperma_2:
	v_writelane_b32 v253, s84, 6
	s_add_u32 s26, s88, 0x1840000
	s_addc_u32 s27, s89, 0
	s_add_u32 s28, s88, 0x4c00000
	s_addc_u32 s29, s89, 0
	s_add_u32 s30, s88, 0x244000
	s_addc_u32 s31, s89, 0
	s_cmpk_lt_i32 s84, 0x80
	s_cselect_b64 s[2:3], -1, 0
	s_cmpk_gt_i32 s84, 0x7f
	s_cselect_b64 s[0:1], -1, 0
	s_add_i32 s14, s92, 0xffffff80
	v_lshlrev_b32_e32 v0, 3, v196
	s_cmpk_lt_u32 s84, 0x80
	v_lshrrev_b32_e32 v199, 6, v196
	v_lshrrev_b32_e32 v200, 3, v196
	v_and_b32_e32 v198, 56, v0
	v_and_b32_e32 v197, 15, v196
	s_cbranch_scc1 .LBB0_521
	s_andn2_b64 vcc, exec, s[0:1]
	s_cbranch_vccnz .LBB0_503
	s_bitcmp0_b32 s84, 8
	s_mov_b32 s15, 0
	s_cbranch_scc1 .LBB0_407
	s_nop 0

.LBB0_698:
	v_readlane_b32 s84, v253, 6
	s_nop 3
	s_add_i32 vcc_lo, s84, 0xffffffc0
	s_cmp_lt_u32 vcc_lo, 64
	s_cbranch_scc0 .Lpermb_1
	s_addk_i32 s84, 0xc0
	s_branch .Lpermb_2

.Lpermb_2:
	v_writelane_b32 v253, s84, 6
	s_cmp_lt_i32 s90, 5
	s_cselect_b64 s[2:3], -1, 0
	s_cmp_gt_i32 s91, 4
	s_cselect_b64 s[0:1], -1, 0
	s_and_b64 s[0:1], s[2:3], s[0:1]
	s_andn2_b64 vcc, exec, s[0:1]
	s_cbranch_vccnz .LBB0_757
	s_andn2_b64 vcc, exec, s[82:83]
	s_cbranch_vccnz .LBB0_753
	s_waitcnt vmcnt(0)
	s_barrier
	s_mov_b64 s[0:1], exec
	v_readlane_b32 s4, v253, 0
	v_readlane_b32 s5, v253, 1
	s_and_b64 s[4:5], s[0:1], s[4:5]
	s_mov_b64 exec, s[4:5]
	s_cbranch_execz .LBB0_752
	v_mov_b32_e32 v0, 0
	s_waitcnt vmcnt(0) expcnt(0) lgkmcnt(0)
	ds_read_b32 v2, v0
	ds_read_b32 v1, v0 offset:4
	s_add_u32 s4, s88, 0xfc00200
	s_addc_u32 s5, s89, 0
	s_waitcnt lgkmcnt(1)
	v_cmp_ne_u32_e32 vcc, 0, v2
	s_cbranch_vccnz .LBB0_716
	s_mul_i32 s33, s93, s92
	v_readlane_b32 s6, v253, 2
	s_mul_i32 s33, s33, s6
	s_add_u32 s6, s88, 0xfc00400
	s_addc_u32 s7, s89, 0
	s_add_u32 s8, s88, 0xfc00500
	s_addc_u32 s9, s89, 0
	s_add_u32 s10, s88, 0xfc00600
	s_addc_u32 s11, s89, 0
	s_add_u32 s12, s88, 0xfc00700
	s_addc_u32 s13, s89, 0
	s_add_u32 s14, s88, 0xfc00800
	s_addc_u32 s15, s89, 0
	s_add_u32 s16, s88, 0xfc00900
	s_addc_u32 s17, s89, 0
	s_add_u32 s18, s88, 0xfc00a00
	s_addc_u32 s19, s89, 0
	s_add_u32 s20, s88, 0xfc00b00
	s_addc_u32 s21, s89, 0
	s_add_u32 s22, s88, 0xfc00c00
	s_addc_u32 s23, s89, 0
	s_add_u32 s24, s88, 0xfc00d00
	s_addc_u32 s25, s89, 0
	s_add_u32 s26, s88, 0xfc00e00
	s_addc_u32 s27, s89, 0
	s_add_u32 s28, s88, 0xfc00f00
	s_addc_u32 s29, s89, 0
	s_add_u32 s30, s88, 0xfc01000
	s_addc_u32 s31, s89, 0
	s_add_u32 s34, s88, 0xfc01100
	s_addc_u32 s35, s89, 0
	s_add_u32 s36, s88, 0xfc01200
	s_addc_u32 s37, s89, 0
	s_add_u32 s38, s88, 0xfc01300
	s_addc_u32 s39, s89, 0
	s_mov_b32 s48, 1
	s_branch .LBB0_704
